# phase 5 inner loop: the 22 load->wait->MFMA blocks pipelined two loads ahead over three register quads with counted vmcnt waits
# baseline (speedup 1.0000x reference)
.LBB0_506:
	s_or_b32 s33, s91, s81
	v_cndmask_b32_e64 v0, 0, 1, s[0:1]
	s_ashr_i32 s1, s33, 31
	s_add_u32 s0, s88, s33
	s_addc_u32 s1, s89, s1
	s_lshl_b64 s[2:3], s[0:1], 10
	s_add_u32 s56, s85, s2
	s_addc_u32 s57, s90, s3
	v_or_b32_e32 v8, s33, v201
	v_cmp_ne_u32_e32 vcc, 1, v0
	v_lshl_add_u64 v[0:1], s[56:57], 0, v[46:47]
	v_lshlrev_b32_e32 v220, 2, v8
	global_load_dwordx4 v[4:7], v[0:1], off
	s_nop 0
	global_load_dwordx4 v[0:3], v[0:1], off offset:64
	ds_read_b32 v9, v220 offset:2048
	v_sub_u32_e32 v29, v8, v202
	global_load_dwordx4 v[12:15], v[68:69], off
	global_load_dwordx4 v[16:19], v[70:71], off
	global_load_dwordx4 v[188:191], v[56:57], off offset:64
	s_waitcnt lgkmcnt(0)
	v_max_f32_e32 v9, v9, v9
	v_max_f32_e32 v221, v219, v9
	v_sub_f32_e32 v9, v216, v221
	v_mul_f32_e32 v28, 0x3fb8aa3b, v9
	global_load_dwordx4 v[8:11], v[56:57], off
	global_load_dwordx4 v[184:187], v[80:81], off
	global_load_dwordx4 v[20:23], v[72:73], off
	global_load_dwordx4 v[24:27], v[74:75], off
	global_load_dwordx4 v[30:33], v[76:77], off
	global_load_dwordx4 v[180:183], v[78:79], off
	s_mul_i32 s2, s1, 0x1900
	s_mul_hi_u32 s3, s0, 0x1900
	s_add_i32 s3, s3, s2
	s_mul_i32 s2, s0, 0x1900
	s_add_u32 s2, s94, s2
	s_addc_u32 s3, s95, s3
	s_add_u32 s2, s2, s72
	s_addc_u32 s3, s3, 0
	s_lshl_b64 s[22:23], s[0:1], 11
	v_cmp_lt_i32_e64 s[0:1], -1, v29
	v_or_b32_e32 v48, s91, v201
	v_exp_f32_e32 v198, v28
	v_lshl_add_u64 v[238:239], s[56:57], 0, v[38:39]
	s_mov_b32 s91, 16
	s_and_b64 vcc, exec, vcc
	s_waitcnt vmcnt(8)
	v_mfma_f32_16x16x32_bf16 v[12:15], v[12:15], v[4:7], 0
	s_waitcnt vmcnt(5)
	v_mfma_f32_16x16x32_bf16 v[8:11], v[8:11], v[4:7], 0
	v_mfma_f32_16x16x32_bf16 v[188:191], v[188:191], v[0:3], v[8:11]
	s_nop 6
	global_load_dwordx4 v[8:11], v[82:83], off
	v_mfma_f32_16x16x32_bf16 v[16:19], v[16:19], v[4:7], 0
	s_waitcnt vmcnt(4)
	v_mfma_f32_16x16x32_bf16 v[20:23], v[20:23], v[4:7], 0
	s_waitcnt vmcnt(3)
	v_mfma_f32_16x16x32_bf16 v[24:27], v[24:27], v[4:7], 0
	s_waitcnt vmcnt(2)
	v_mfma_f32_16x16x32_bf16 v[30:33], v[30:33], v[4:7], 0
	s_waitcnt vmcnt(1)
	v_mfma_f32_16x16x32_bf16 v[180:183], v[180:183], v[4:7], 0
	v_mfma_f32_16x16x32_bf16 v[184:187], v[184:187], v[4:7], 0
	s_waitcnt vmcnt(0)
	v_mfma_f32_16x16x32_bf16 v[192:195], v[8:11], v[0:3], v[12:15]
	global_load_dwordx4 v[8:11], v[84:85], off
	s_waitcnt vmcnt(0)
	v_mfma_f32_16x16x32_bf16 v[222:225], v[8:11], v[0:3], v[16:19]
	global_load_dwordx4 v[8:11], v[86:87], off
	s_waitcnt vmcnt(0)
	v_mfma_f32_16x16x32_bf16 v[226:229], v[8:11], v[0:3], v[20:23]
	global_load_dwordx4 v[8:11], v[88:89], off
	s_waitcnt vmcnt(0)
	v_mfma_f32_16x16x32_bf16 v[20:23], v[8:11], v[0:3], v[24:27]
	global_load_dwordx4 v[8:11], v[90:91], off
	s_nop 1
	ds_read_b128 v[24:27], v36 offset:1536
	s_waitcnt lgkmcnt(0)
	v_sub_f32_e32 v24, v24, v221
	v_mul_f32_e32 v24, 0x3fb8aa3b, v24
	v_sub_f32_e32 v25, v25, v221
	v_cndmask_b32_e64 v24, v37, v24, s[0:1]
	v_mul_f32_e32 v25, 0x3fb8aa3b, v25
	v_cmp_lt_i32_e64 s[0:1], 0, v29
	v_sub_f32_e32 v26, v26, v221
	v_mul_f32_e32 v26, 0x3fb8aa3b, v26
	v_cndmask_b32_e64 v25, v37, v25, s[0:1]
	v_cmp_lt_i32_e64 s[0:1], 1, v29
	v_sub_f32_e32 v27, v27, v221
	v_mul_f32_e32 v27, 0x3fb8aa3b, v27
	v_cndmask_b32_e64 v26, v37, v26, s[0:1]
	v_cmp_lt_i32_e64 s[0:1], 2, v29
	v_exp_f32_e32 v24, v24
	v_exp_f32_e32 v25, v25
	v_cndmask_b32_e64 v27, v37, v27, s[0:1]
	v_exp_f32_e32 v26, v26
	v_exp_f32_e32 v27, v27
	v_pk_mul_f32 v[24:25], v[188:189], v[24:25]
	v_cmp_lt_i32_e64 s[0:1], 15, v29
	s_waitcnt vmcnt(0)
	v_mfma_f32_16x16x32_bf16 v[16:19], v[8:11], v[0:3], v[30:33]
	global_load_dwordx4 v[8:11], v[92:93], off
	s_nop 1
	v_add_f32_e32 v31, 0, v24
	v_pk_mul_f32 v[26:27], v[190:191], v[26:27]
	v_mad_u32_u24 v30, v48, s86, v204
	v_add_f32_e32 v31, v25, v31
	v_cvt_pk_bf16_f32 v24, v24, v25
	v_cvt_pk_bf16_f32 v25, v26, v27
	v_add_f32_e32 v31, v26, v31
	ds_write_b64 v30, v[24:25] offset:4096
	v_add_f32_e32 v31, v27, v31
	ds_read_b128 v[24:27], v36 offset:1600
	v_mad_u32_u24 v48, v48, s86, v205
	s_waitcnt vmcnt(0)
	v_mfma_f32_16x16x32_bf16 v[12:15], v[8:11], v[0:3], v[180:183]
	global_load_dwordx4 v[8:11], v[94:95], off
	s_waitcnt lgkmcnt(0)
	v_sub_f32_e32 v24, v24, v221
	v_mul_f32_e32 v24, 0x3fb8aa3b, v24
	v_sub_f32_e32 v25, v25, v221
	v_cndmask_b32_e64 v24, v37, v24, s[0:1]
	v_mul_f32_e32 v25, 0x3fb8aa3b, v25
	v_cmp_lt_i32_e64 s[0:1], 16, v29
	v_sub_f32_e32 v26, v26, v221
	v_mul_f32_e32 v26, 0x3fb8aa3b, v26
	v_cndmask_b32_e64 v25, v37, v25, s[0:1]
	v_cmp_lt_i32_e64 s[0:1], 17, v29
	v_sub_f32_e32 v27, v27, v221
	v_mul_f32_e32 v27, 0x3fb8aa3b, v27
	v_cndmask_b32_e64 v26, v37, v26, s[0:1]
	v_cmp_lt_i32_e64 s[0:1], 18, v29
	v_exp_f32_e32 v24, v24
	v_exp_f32_e32 v25, v25
	v_cndmask_b32_e64 v27, v37, v27, s[0:1]
	v_exp_f32_e32 v26, v26
	v_exp_f32_e32 v27, v27
	v_pk_mul_f32 v[24:25], v[192:193], v[24:25]
	v_cmp_lt_i32_e64 s[0:1], 31, v29
	v_add_f32_e32 v31, v24, v31
	v_pk_mul_f32 v[26:27], v[194:195], v[26:27]
	v_add_f32_e32 v31, v25, v31
	v_cvt_pk_bf16_f32 v24, v24, v25
	v_cvt_pk_bf16_f32 v25, v26, v27
	v_add_f32_e32 v31, v26, v31
	ds_write_b64 v30, v[24:25] offset:4128
	v_add_f32_e32 v31, v27, v31
	ds_read_b128 v[24:27], v36 offset:1664
	s_waitcnt vmcnt(0)
	v_mfma_f32_16x16x32_bf16 v[8:11], v[8:11], v[0:3], v[184:187]
	s_waitcnt lgkmcnt(0)
	v_sub_f32_e32 v24, v24, v221
	v_mul_f32_e32 v24, 0x3fb8aa3b, v24
	v_sub_f32_e32 v25, v25, v221
	v_cndmask_b32_e64 v24, v37, v24, s[0:1]
	v_mul_f32_e32 v25, 0x3fb8aa3b, v25
	v_cmp_lt_i32_e64 s[0:1], 32, v29
	v_sub_f32_e32 v26, v26, v221
	v_mul_f32_e32 v26, 0x3fb8aa3b, v26
	v_cndmask_b32_e64 v25, v37, v25, s[0:1]
	v_cmp_lt_i32_e64 s[0:1], 33, v29
	v_sub_f32_e32 v27, v27, v221
	v_mul_f32_e32 v27, 0x3fb8aa3b, v27
	v_cndmask_b32_e64 v26, v37, v26, s[0:1]
	v_cmp_lt_i32_e64 s[0:1], 34, v29
	v_exp_f32_e32 v24, v24
	v_exp_f32_e32 v25, v25
	v_cndmask_b32_e64 v27, v37, v27, s[0:1]
	v_exp_f32_e32 v26, v26
	v_exp_f32_e32 v27, v27
	v_pk_mul_f32 v[24:25], v[222:223], v[24:25]
	v_cmp_lt_i32_e64 s[0:1], 47, v29
	v_add_f32_e32 v31, v24, v31
	v_pk_mul_f32 v[26:27], v[224:225], v[26:27]
	v_add_f32_e32 v31, v25, v31
	v_cvt_pk_bf16_f32 v24, v24, v25
	v_cvt_pk_bf16_f32 v25, v26, v27
	v_add_f32_e32 v31, v26, v31
	ds_write_b64 v30, v[24:25] offset:4160
	v_add_f32_e32 v31, v27, v31
	ds_read_b128 v[24:27], v36 offset:1728
	s_waitcnt lgkmcnt(0)
	v_sub_f32_e32 v24, v24, v221
	v_mul_f32_e32 v24, 0x3fb8aa3b, v24
	v_sub_f32_e32 v25, v25, v221
	v_cndmask_b32_e64 v24, v37, v24, s[0:1]
	v_mul_f32_e32 v25, 0x3fb8aa3b, v25
	v_cmp_lt_i32_e64 s[0:1], 48, v29
	v_sub_f32_e32 v26, v26, v221
	v_mul_f32_e32 v26, 0x3fb8aa3b, v26
	v_cndmask_b32_e64 v25, v37, v25, s[0:1]
	v_cmp_lt_i32_e64 s[0:1], 49, v29
	v_sub_f32_e32 v27, v27, v221
	v_mul_f32_e32 v27, 0x3fb8aa3b, v27
	v_cndmask_b32_e64 v26, v37, v26, s[0:1]
	v_cmp_lt_i32_e64 s[0:1], 50, v29
	v_exp_f32_e32 v24, v24
	v_exp_f32_e32 v25, v25
	v_cndmask_b32_e64 v27, v37, v27, s[0:1]
	v_exp_f32_e32 v26, v26
	v_exp_f32_e32 v27, v27
	v_pk_mul_f32 v[24:25], v[226:227], v[24:25]
	v_cmp_lt_i32_e64 s[0:1], 63, v29
	v_add_f32_e32 v31, v24, v31
	v_pk_mul_f32 v[26:27], v[228:229], v[26:27]
	v_add_f32_e32 v31, v25, v31
	v_cvt_pk_bf16_f32 v24, v24, v25
	v_cvt_pk_bf16_f32 v25, v26, v27
	v_add_f32_e32 v31, v26, v31
	ds_write_b64 v30, v[24:25] offset:4192
	v_add_f32_e32 v180, v27, v31
	ds_read_b128 v[24:27], v36 offset:1792
	s_waitcnt lgkmcnt(0)
	v_sub_f32_e32 v24, v24, v221
	v_mul_f32_e32 v24, 0x3fb8aa3b, v24
	v_sub_f32_e32 v25, v25, v221
	v_cndmask_b32_e64 v24, v37, v24, s[0:1]
	v_mul_f32_e32 v25, 0x3fb8aa3b, v25
	v_cmp_lt_i32_e64 s[0:1], 64, v29
	v_exp_f32_e32 v24, v24
	s_nop 0
	v_cndmask_b32_e64 v25, v37, v25, s[0:1]
	v_exp_f32_e32 v25, v25
	s_movk_i32 s0, 0x41
	v_cmp_lt_i32_e64 s[0:1], s0, v29
	v_pk_mul_f32 v[182:183], v[20:21], v[24:25]
	v_sub_f32_e32 v20, v26, v221
	v_mul_f32_e32 v20, 0x3fb8aa3b, v20
	v_cndmask_b32_e64 v20, v37, v20, s[0:1]
	v_sub_f32_e32 v21, v27, v221
	s_movk_i32 s0, 0x42
	v_mul_f32_e32 v21, 0x3fb8aa3b, v21
	v_cmp_lt_i32_e64 s[0:1], s0, v29
	v_exp_f32_e32 v20, v20
	s_nop 0
	v_cndmask_b32_e64 v21, v37, v21, s[0:1]
	v_exp_f32_e32 v21, v21
	s_movk_i32 s0, 0x4f
	v_cmp_lt_i32_e64 s[0:1], s0, v29
	v_pk_mul_f32 v[184:185], v[22:23], v[20:21]
	v_cvt_pk_bf16_f32 v20, v182, v183
	v_cvt_pk_bf16_f32 v21, v184, v185
	ds_write_b64 v30, v[20:21] offset:4224
	ds_read_b128 v[20:23], v36 offset:1856
	v_mov_b32_e32 v240, v184
	s_waitcnt lgkmcnt(0)
	v_sub_f32_e32 v20, v20, v221
	v_mul_f32_e32 v20, 0x3fb8aa3b, v20
	v_cndmask_b32_e64 v20, v37, v20, s[0:1]
	v_sub_f32_e32 v21, v21, v221
	s_movk_i32 s0, 0x50
	v_mul_f32_e32 v21, 0x3fb8aa3b, v21
	v_cmp_lt_i32_e64 s[0:1], s0, v29
	v_exp_f32_e32 v20, v20
	s_nop 0
	v_cndmask_b32_e64 v21, v37, v21, s[0:1]
	v_exp_f32_e32 v21, v21
	s_movk_i32 s0, 0x51
	v_cmp_lt_i32_e64 s[0:1], s0, v29
	v_pk_mul_f32 v[186:187], v[16:17], v[20:21]
	v_sub_f32_e32 v16, v22, v221
	v_mul_f32_e32 v16, 0x3fb8aa3b, v16
	v_cndmask_b32_e64 v16, v37, v16, s[0:1]
	v_sub_f32_e32 v17, v23, v221
	s_movk_i32 s0, 0x52
	v_mul_f32_e32 v17, 0x3fb8aa3b, v17
	v_cmp_lt_i32_e64 s[0:1], s0, v29
	v_exp_f32_e32 v16, v16
	s_nop 0
	v_cndmask_b32_e64 v17, v37, v17, s[0:1]
	v_exp_f32_e32 v17, v17
	s_movk_i32 s0, 0x5f
	v_cmp_lt_i32_e64 s[0:1], s0, v29
	v_pk_mul_f32 v[188:189], v[18:19], v[16:17]
	v_cvt_pk_bf16_f32 v16, v186, v187
	v_cvt_pk_bf16_f32 v17, v188, v189
	ds_write_b64 v30, v[16:17] offset:4256
	ds_read_b128 v[16:19], v36 offset:1920
	v_mov_b32_e32 v184, v189
	s_waitcnt lgkmcnt(0)
	v_sub_f32_e32 v16, v16, v221
	v_mul_f32_e32 v16, 0x3fb8aa3b, v16
	v_cndmask_b32_e64 v16, v37, v16, s[0:1]
	v_sub_f32_e32 v17, v17, v221
	s_movk_i32 s0, 0x60
	v_mul_f32_e32 v17, 0x3fb8aa3b, v17
	v_cmp_lt_i32_e64 s[0:1], s0, v29
	v_exp_f32_e32 v16, v16
	s_nop 0
	v_cndmask_b32_e64 v17, v37, v17, s[0:1]
	v_exp_f32_e32 v17, v17
	s_movk_i32 s0, 0x61
	v_cmp_lt_i32_e64 s[0:1], s0, v29
	v_pk_mul_f32 v[190:191], v[12:13], v[16:17]
	v_sub_f32_e32 v12, v18, v221
	v_mul_f32_e32 v12, 0x3fb8aa3b, v12
	v_cndmask_b32_e64 v12, v37, v12, s[0:1]
	v_sub_f32_e32 v13, v19, v221
	s_movk_i32 s0, 0x62
	v_mul_f32_e32 v13, 0x3fb8aa3b, v13
	v_cmp_lt_i32_e64 s[0:1], s0, v29
	v_exp_f32_e32 v12, v12
	s_nop 0
	v_cndmask_b32_e64 v13, v37, v13, s[0:1]
	v_exp_f32_e32 v13, v13
	s_movk_i32 s0, 0x6f
	v_cmp_lt_i32_e64 s[0:1], s0, v29
	v_pk_mul_f32 v[192:193], v[14:15], v[12:13]
	v_cvt_pk_bf16_f32 v12, v190, v191
	v_cvt_pk_bf16_f32 v13, v192, v193
	ds_write_b64 v30, v[12:13] offset:4288
	ds_read_b128 v[12:15], v36 offset:1984
	s_waitcnt lgkmcnt(0)
	v_sub_f32_e32 v12, v12, v221
	v_mul_f32_e32 v12, 0x3fb8aa3b, v12
	v_cndmask_b32_e64 v12, v37, v12, s[0:1]
	v_sub_f32_e32 v13, v13, v221
	s_movk_i32 s0, 0x70
	v_mul_f32_e32 v13, 0x3fb8aa3b, v13
	v_cmp_lt_i32_e64 s[0:1], s0, v29
	v_exp_f32_e32 v12, v12
	s_nop 0
	v_cndmask_b32_e64 v13, v37, v13, s[0:1]
	v_exp_f32_e32 v13, v13
	s_movk_i32 s0, 0x71
	v_cmp_lt_i32_e64 s[0:1], s0, v29
	v_pk_mul_f32 v[194:195], v[8:9], v[12:13]
	v_sub_f32_e32 v8, v14, v221
	v_mul_f32_e32 v8, 0x3fb8aa3b, v8
	v_cndmask_b32_e64 v8, v37, v8, s[0:1]
	v_sub_f32_e32 v9, v15, v221
	s_movk_i32 s0, 0x72
	v_mul_f32_e32 v9, 0x3fb8aa3b, v9
	v_cmp_lt_i32_e64 s[0:1], s0, v29
	v_exp_f32_e32 v8, v8
	s_nop 0
	v_cndmask_b32_e64 v9, v37, v9, s[0:1]
	v_exp_f32_e32 v9, v9
	s_nop 0
	v_pk_mul_f32 v[196:197], v[10:11], v[8:9]
	v_cvt_pk_bf16_f32 v8, v194, v195
	v_cvt_pk_bf16_f32 v9, v196, v197
	ds_write_b64 v30, v[8:9] offset:4320
	s_waitcnt lgkmcnt(0)
	s_barrier
	global_load_dwordx4 v[8:11], v[62:63], off offset:16
	global_load_dwordx4 v[12:15], v[62:63], off
	s_waitcnt vmcnt(1)
	v_cvt_pk_bf16_f32 v9, v9, v10
	s_waitcnt vmcnt(0)
	v_cvt_pk_bf16_f32 v12, v12, s0
	v_cvt_pk_bf16_f32 v13, v13, v14
	v_cvt_pk_bf16_f32 v8, v15, v8
	v_perm_b32 v12, v13, v12, s87
	v_alignbit_b32 v13, v8, v13, 16
	v_alignbit_b32 v14, v9, v8, 16
	v_cvt_pk_bf16_f32 v8, v11, s0
	v_alignbit_b32 v15, v8, v9, 16
	s_nop 1
	v_mfma_f32_16x16x32_bf16 v[32:35], v[12:15], v[4:7], 0
	global_load_dwordx4 v[8:11], v[96:97], off offset:16
	global_load_dwordx4 v[12:15], v[96:97], off
	s_waitcnt vmcnt(1)
	v_cvt_pk_bf16_f32 v9, v9, v10
	s_waitcnt vmcnt(0)
	v_cvt_pk_bf16_f32 v12, v12, s0
	v_cvt_pk_bf16_f32 v13, v13, v14
	v_cvt_pk_bf16_f32 v8, v15, v8
	v_perm_b32 v12, v13, v12, s87
	v_alignbit_b32 v13, v8, v13, 16
	v_alignbit_b32 v14, v9, v8, 16
	v_cvt_pk_bf16_f32 v8, v11, s0
	v_alignbit_b32 v15, v8, v9, 16
	s_nop 1
	v_mfma_f32_16x16x32_bf16 v[28:31], v[12:15], v[4:7], 0
	global_load_dwordx4 v[8:11], v[98:99], off offset:16
	global_load_dwordx4 v[12:15], v[98:99], off
	s_waitcnt vmcnt(1)
	v_cvt_pk_bf16_f32 v9, v9, v10
	s_waitcnt vmcnt(0)
	v_cvt_pk_bf16_f32 v12, v12, s0
	v_cvt_pk_bf16_f32 v13, v13, v14
	v_cvt_pk_bf16_f32 v8, v15, v8
	v_perm_b32 v12, v13, v12, s87
	v_alignbit_b32 v13, v8, v13, 16
	v_alignbit_b32 v14, v9, v8, 16
	v_cvt_pk_bf16_f32 v8, v11, s0
	v_alignbit_b32 v15, v8, v9, 16
	s_nop 1
	v_mfma_f32_16x16x32_bf16 v[24:27], v[12:15], v[4:7], 0
	global_load_dwordx4 v[8:11], v[100:101], off offset:16
	global_load_dwordx4 v[12:15], v[100:101], off
	s_waitcnt vmcnt(1)
	v_cvt_pk_bf16_f32 v9, v9, v10
	s_waitcnt vmcnt(0)
	v_cvt_pk_bf16_f32 v12, v12, s0
	v_cvt_pk_bf16_f32 v13, v13, v14
	v_cvt_pk_bf16_f32 v8, v15, v8
	v_perm_b32 v12, v13, v12, s87
	v_alignbit_b32 v13, v8, v13, 16
	v_alignbit_b32 v14, v9, v8, 16
	v_cvt_pk_bf16_f32 v8, v11, s0
	v_alignbit_b32 v15, v8, v9, 16
	s_nop 1
	v_mfma_f32_16x16x32_bf16 v[8:11], v[12:15], v[4:7], 0
	global_load_dwordx4 v[12:15], v[102:103], off offset:16
	global_load_dwordx4 v[16:19], v[102:103], off
	s_waitcnt vmcnt(1)
	v_cvt_pk_bf16_f32 v13, v13, v14
	s_waitcnt vmcnt(0)
	v_cvt_pk_bf16_f32 v16, v16, s0
	v_cvt_pk_bf16_f32 v17, v17, v18
	v_cvt_pk_bf16_f32 v12, v19, v12
	v_perm_b32 v16, v17, v16, s87
	v_alignbit_b32 v17, v12, v17, 16
	v_alignbit_b32 v18, v13, v12, 16
	v_cvt_pk_bf16_f32 v12, v15, s0
	v_alignbit_b32 v19, v12, v13, 16
	s_nop 1
	v_mfma_f32_16x16x32_bf16 v[12:15], v[16:19], v[4:7], 0
	global_load_dwordx4 v[16:19], v[104:105], off offset:16
	global_load_dwordx4 v[20:23], v[104:105], off
	s_waitcnt vmcnt(1)
	v_cvt_pk_bf16_f32 v17, v17, v18
	s_waitcnt vmcnt(0)
	v_cvt_pk_bf16_f32 v20, v20, s0
	v_cvt_pk_bf16_f32 v21, v21, v22
	v_cvt_pk_bf16_f32 v16, v23, v16
	v_perm_b32 v20, v21, v20, s87
	v_alignbit_b32 v21, v16, v21, 16
	v_alignbit_b32 v22, v17, v16, 16
	v_cvt_pk_bf16_f32 v16, v19, s0
	v_alignbit_b32 v23, v16, v17, 16
	s_nop 1
	v_mfma_f32_16x16x32_bf16 v[16:19], v[20:23], v[4:7], 0
	global_load_dwordx4 v[20:23], v[106:107], off offset:16
	global_load_dwordx4 v[222:225], v[106:107], off
	s_waitcnt vmcnt(1)
	v_cvt_pk_bf16_f32 v21, v21, v22
	s_waitcnt vmcnt(0)
	v_cvt_pk_bf16_f32 v181, v222, s0
	v_cvt_pk_bf16_f32 v223, v223, v224
	v_cvt_pk_bf16_f32 v20, v225, v20
	v_perm_b32 v222, v223, v181, s87
	v_alignbit_b32 v223, v20, v223, 16
	v_alignbit_b32 v224, v21, v20, 16
	v_cvt_pk_bf16_f32 v20, v23, s0
	v_alignbit_b32 v225, v20, v21, 16
	s_nop 1
	v_mfma_f32_16x16x32_bf16 v[20:23], v[222:225], v[4:7], 0
	global_load_dwordx4 v[222:225], v[108:109], off offset:16
	global_load_dwordx4 v[226:229], v[108:109], off
	s_waitcnt vmcnt(0)
	v_cvt_pk_bf16_f32 v181, v226, s0
	v_cvt_pk_bf16_f32 v227, v227, v228
	v_perm_b32 v226, v227, v181, s87
	v_cvt_pk_bf16_f32 v181, v229, v222
	v_cvt_pk_bf16_f32 v222, v223, v224
	v_alignbit_b32 v227, v181, v227, 16
	v_alignbit_b32 v228, v222, v181, 16
	v_cvt_pk_bf16_f32 v181, v225, s0
	v_alignbit_b32 v229, v181, v222, 16
	s_nop 1
	v_mfma_f32_16x16x32_bf16 v[4:7], v[226:229], v[4:7], 0
	global_load_dwordx4 v[222:225], v[62:63], off offset:144
	global_load_dwordx4 v[226:229], v[62:63], off offset:128
	s_waitcnt vmcnt(0)
	v_cvt_pk_bf16_f32 v181, v226, s0
	v_cvt_pk_bf16_f32 v227, v227, v228
	v_perm_b32 v226, v227, v181, s87
	v_cvt_pk_bf16_f32 v181, v229, v222
	v_cvt_pk_bf16_f32 v222, v223, v224
	v_alignbit_b32 v227, v181, v227, 16
	v_alignbit_b32 v228, v222, v181, 16
	v_cvt_pk_bf16_f32 v181, v225, s0
	v_alignbit_b32 v229, v181, v222, 16
	s_nop 1
	v_mfma_f32_16x16x32_bf16 v[32:35], v[226:229], v[0:3], v[32:35]
	global_load_dwordx4 v[222:225], v[110:111], off offset:16
	global_load_dwordx4 v[226:229], v[110:111], off
	s_waitcnt vmcnt(0)
	v_cvt_pk_bf16_f32 v181, v226, s0
	v_cvt_pk_bf16_f32 v227, v227, v228
	v_perm_b32 v226, v227, v181, s87
	v_cvt_pk_bf16_f32 v181, v229, v222
	v_cvt_pk_bf16_f32 v222, v223, v224
	v_alignbit_b32 v227, v181, v227, 16
	v_alignbit_b32 v228, v222, v181, 16
	v_cvt_pk_bf16_f32 v181, v225, s0
	v_alignbit_b32 v229, v181, v222, 16
	v_pk_mul_f32 v[34:35], v[198:199], v[34:35] op_sel_hi:[0,1]
	v_pk_mul_f32 v[32:33], v[198:199], v[32:33] op_sel_hi:[0,1]
	v_mfma_f32_16x16x32_bf16 v[28:31], v[226:229], v[0:3], v[28:31]
	global_load_dwordx4 v[222:225], v[112:113], off offset:16
	global_load_dwordx4 v[226:229], v[112:113], off
	s_waitcnt vmcnt(0)
	v_cvt_pk_bf16_f32 v181, v226, s0
	v_cvt_pk_bf16_f32 v227, v227, v228
	v_perm_b32 v226, v227, v181, s87
	v_cvt_pk_bf16_f32 v181, v229, v222
	v_cvt_pk_bf16_f32 v222, v223, v224
	v_alignbit_b32 v227, v181, v227, 16
	v_alignbit_b32 v228, v222, v181, 16
	v_cvt_pk_bf16_f32 v181, v225, s0
	v_alignbit_b32 v229, v181, v222, 16
	v_pk_mul_f32 v[30:31], v[198:199], v[30:31] op_sel_hi:[0,1]
	v_pk_mul_f32 v[28:29], v[198:199], v[28:29] op_sel_hi:[0,1]
	v_mfma_f32_16x16x32_bf16 v[24:27], v[226:229], v[0:3], v[24:27]
	global_load_dwordx4 v[222:225], v[114:115], off offset:16
	global_load_dwordx4 v[226:229], v[114:115], off
	s_waitcnt vmcnt(0)
	v_cvt_pk_bf16_f32 v181, v226, s0
	v_cvt_pk_bf16_f32 v227, v227, v228
	v_perm_b32 v226, v227, v181, s87
	v_cvt_pk_bf16_f32 v181, v229, v222
	v_cvt_pk_bf16_f32 v222, v223, v224
	v_alignbit_b32 v227, v181, v227, 16
	v_alignbit_b32 v228, v222, v181, 16
	v_cvt_pk_bf16_f32 v181, v225, s0
	v_alignbit_b32 v229, v181, v222, 16
	v_pk_mul_f32 v[26:27], v[198:199], v[26:27] op_sel_hi:[0,1]
	v_pk_mul_f32 v[24:25], v[198:199], v[24:25] op_sel_hi:[0,1]
	v_mfma_f32_16x16x32_bf16 v[8:11], v[226:229], v[0:3], v[8:11]
	global_load_dwordx4 v[222:225], v[116:117], off offset:16
	global_load_dwordx4 v[226:229], v[116:117], off
	s_waitcnt vmcnt(0)
	v_cvt_pk_bf16_f32 v181, v226, s0
	v_cvt_pk_bf16_f32 v227, v227, v228
	v_perm_b32 v226, v227, v181, s87
	v_cvt_pk_bf16_f32 v181, v229, v222
	v_cvt_pk_bf16_f32 v222, v223, v224
	v_alignbit_b32 v227, v181, v227, 16
	v_alignbit_b32 v228, v222, v181, 16
	v_cvt_pk_bf16_f32 v181, v225, s0
	v_alignbit_b32 v229, v181, v222, 16
	v_pk_mul_f32 v[10:11], v[198:199], v[10:11] op_sel_hi:[0,1]
	v_pk_mul_f32 v[8:9], v[198:199], v[8:9] op_sel_hi:[0,1]
	v_mfma_f32_16x16x32_bf16 v[12:15], v[226:229], v[0:3], v[12:15]
	global_load_dwordx4 v[222:225], v[118:119], off offset:16
	global_load_dwordx4 v[226:229], v[118:119], off
	s_waitcnt vmcnt(0)
	v_cvt_pk_bf16_f32 v181, v226, s0
	v_cvt_pk_bf16_f32 v227, v227, v228
	v_perm_b32 v226, v227, v181, s87
	v_cvt_pk_bf16_f32 v181, v229, v222
	v_cvt_pk_bf16_f32 v222, v223, v224
	v_alignbit_b32 v227, v181, v227, 16
	v_alignbit_b32 v228, v222, v181, 16
	v_cvt_pk_bf16_f32 v181, v225, s0
	v_alignbit_b32 v229, v181, v222, 16
	v_pk_mul_f32 v[14:15], v[198:199], v[14:15] op_sel_hi:[0,1]
	v_pk_mul_f32 v[12:13], v[198:199], v[12:13] op_sel_hi:[0,1]
	v_mfma_f32_16x16x32_bf16 v[16:19], v[226:229], v[0:3], v[16:19]
	global_load_dwordx4 v[222:225], v[120:121], off offset:16
	global_load_dwordx4 v[226:229], v[120:121], off
	s_waitcnt vmcnt(0)
	v_cvt_pk_bf16_f32 v181, v226, s0
	v_cvt_pk_bf16_f32 v227, v227, v228
	v_perm_b32 v226, v227, v181, s87
	v_cvt_pk_bf16_f32 v181, v229, v222
	v_cvt_pk_bf16_f32 v222, v223, v224
	v_alignbit_b32 v227, v181, v227, 16
	v_alignbit_b32 v228, v222, v181, 16
	v_cvt_pk_bf16_f32 v181, v225, s0
	v_alignbit_b32 v229, v181, v222, 16
	v_pk_mul_f32 v[18:19], v[198:199], v[18:19] op_sel_hi:[0,1]
	v_pk_mul_f32 v[16:17], v[198:199], v[16:17] op_sel_hi:[0,1]
	v_mfma_f32_16x16x32_bf16 v[20:23], v[226:229], v[0:3], v[20:23]
	global_load_dwordx4 v[222:225], v[122:123], off offset:16
	global_load_dwordx4 v[226:229], v[122:123], off
	ds_read_b128 v[230:233], v48 offset:4288
	s_nop 4
	v_pk_mul_f32 v[22:23], v[198:199], v[22:23] op_sel_hi:[0,1]
	v_pk_mul_f32 v[20:21], v[198:199], v[20:21] op_sel_hi:[0,1]
	s_waitcnt vmcnt(0)
	v_cvt_pk_bf16_f32 v181, v226, s0
	v_cvt_pk_bf16_f32 v227, v227, v228
	v_perm_b32 v226, v227, v181, s87
	v_cvt_pk_bf16_f32 v181, v229, v222
	v_cvt_pk_bf16_f32 v222, v223, v224
	v_alignbit_b32 v227, v181, v227, 16
	v_alignbit_b32 v228, v222, v181, 16
	v_cvt_pk_bf16_f32 v181, v225, s0
	v_alignbit_b32 v229, v181, v222, 16
	global_load_dwordx4 v[222:225], v[58:59], off
	global_load_dwordx4 v[244:247], v[124:125], off
	global_load_dwordx4 v[248:251], v[126:127], off
	s_mov_b64 s[0:1], 0x6c01020
	v_mfma_f32_16x16x32_bf16 v[0:3], v[226:229], v[0:3], v[4:7]
	s_nop 2
	ds_read_b128 v[4:7], v48 offset:4096
	s_waitcnt vmcnt(2) lgkmcnt(0)
	v_mfma_f32_16x16x32_bf16 v[32:35], v[222:225], v[4:7], v[32:35]
	global_load_dwordx4 v[222:225], v[128:129], off
	s_nop 0
	v_pk_mul_f32 v[2:3], v[198:199], v[2:3] op_sel_hi:[0,1]
	v_pk_mul_f32 v[0:1], v[198:199], v[0:1] op_sel_hi:[0,1]
	s_waitcnt vmcnt(2)
	v_mfma_f32_16x16x32_bf16 v[28:31], v[244:247], v[4:7], v[28:31]
	global_load_dwordx4 v[244:247], v[130:131], off
	s_waitcnt vmcnt(2)
	v_mfma_f32_16x16x32_bf16 v[24:27], v[248:251], v[4:7], v[24:27]
	global_load_dwordx4 v[248:251], v[132:133], off
	s_waitcnt vmcnt(2)
	v_mfma_f32_16x16x32_bf16 v[8:11], v[222:225], v[4:7], v[8:11]
	global_load_dwordx4 v[222:225], v[134:135], off
	s_waitcnt vmcnt(2)
	v_mfma_f32_16x16x32_bf16 v[12:15], v[244:247], v[4:7], v[12:15]
	global_load_dwordx4 v[244:247], v[136:137], off
	s_waitcnt vmcnt(2)
	v_mfma_f32_16x16x32_bf16 v[16:19], v[248:251], v[4:7], v[16:19]
	global_load_dwordx4 v[248:251], v[58:59], off offset:64
	s_waitcnt vmcnt(2)
	v_mfma_f32_16x16x32_bf16 v[20:23], v[222:225], v[4:7], v[20:23]
	global_load_dwordx4 v[222:225], v[138:139], off
	s_waitcnt vmcnt(2)
	v_mfma_f32_16x16x32_bf16 v[0:3], v[244:247], v[4:7], v[0:3]
	global_load_dwordx4 v[244:247], v[140:141], off
	ds_read_b128 v[4:7], v48 offset:4160
	s_waitcnt vmcnt(2) lgkmcnt(0)
	v_mfma_f32_16x16x32_bf16 v[32:35], v[248:251], v[4:7], v[32:35]
	global_load_dwordx4 v[248:251], v[142:143], off
	s_waitcnt vmcnt(2)
	v_mfma_f32_16x16x32_bf16 v[28:31], v[222:225], v[4:7], v[28:31]
	global_load_dwordx4 v[222:225], v[144:145], off
	s_waitcnt vmcnt(2)
	v_mfma_f32_16x16x32_bf16 v[24:27], v[244:247], v[4:7], v[24:27]
	global_load_dwordx4 v[244:247], v[146:147], off
	s_waitcnt vmcnt(2)
	v_mfma_f32_16x16x32_bf16 v[8:11], v[248:251], v[4:7], v[8:11]
	global_load_dwordx4 v[248:251], v[148:149], off
	s_waitcnt vmcnt(2)
	v_mfma_f32_16x16x32_bf16 v[12:15], v[222:225], v[4:7], v[12:15]
	global_load_dwordx4 v[222:225], v[150:151], off
	s_waitcnt vmcnt(2)
	v_mfma_f32_16x16x32_bf16 v[16:19], v[244:247], v[4:7], v[16:19]
	global_load_dwordx4 v[244:247], v[58:59], off offset:128
	s_waitcnt vmcnt(2)
	v_mfma_f32_16x16x32_bf16 v[20:23], v[248:251], v[4:7], v[20:23]
	global_load_dwordx4 v[248:251], v[152:153], off
	s_waitcnt vmcnt(2)
	v_mfma_f32_16x16x32_bf16 v[0:3], v[222:225], v[4:7], v[0:3]
	global_load_dwordx4 v[222:225], v[154:155], off
	ds_read_b128 v[4:7], v48 offset:4224
	s_waitcnt vmcnt(2) lgkmcnt(0)
	v_mfma_f32_16x16x32_bf16 v[32:35], v[244:247], v[4:7], v[32:35]
	global_load_dwordx4 v[244:247], v[156:157], off
	s_waitcnt vmcnt(2)
	v_mfma_f32_16x16x32_bf16 v[28:31], v[248:251], v[4:7], v[28:31]
	global_load_dwordx4 v[248:251], v[158:159], off
	s_waitcnt vmcnt(2)
	v_mfma_f32_16x16x32_bf16 v[24:27], v[222:225], v[4:7], v[24:27]
	global_load_dwordx4 v[222:225], v[160:161], off
	s_waitcnt vmcnt(2)
	v_mfma_f32_16x16x32_bf16 v[8:11], v[244:247], v[4:7], v[8:11]
	s_waitcnt vmcnt(1)
	v_mfma_f32_16x16x32_bf16 v[12:15], v[248:251], v[4:7], v[12:15]
	s_waitcnt vmcnt(0)
	v_mfma_f32_16x16x32_bf16 v[222:225], v[222:225], v[4:7], v[16:19]
	s_nop 2
	global_load_dwordx4 v[16:19], v[162:163], off
	s_waitcnt vmcnt(0)
	v_mfma_f32_16x16x32_bf16 v[226:229], v[16:19], v[4:7], v[20:23]
	global_load_dwordx4 v[16:19], v[164:165], off
	s_waitcnt vmcnt(0)
	v_mfma_f32_16x16x32_bf16 v[0:3], v[16:19], v[4:7], v[0:3]
	global_load_dwordx4 v[4:7], v[58:59], off offset:192
	s_waitcnt vmcnt(0)
	v_mfma_f32_16x16x32_bf16 v[32:35], v[4:7], v[230:233], v[32:35]
	global_load_dwordx4 v[4:7], v[166:167], off
	s_waitcnt vmcnt(0)
	v_mfma_f32_16x16x32_bf16 v[28:31], v[4:7], v[230:233], v[28:31]
	global_load_dwordx4 v[4:7], v[168:169], off
	s_waitcnt vmcnt(0)
	v_mfma_f32_16x16x32_bf16 v[24:27], v[4:7], v[230:233], v[24:27]
	global_load_dwordx4 v[4:7], v[170:171], off
	s_waitcnt vmcnt(0)
	v_mfma_f32_16x16x32_bf16 v[20:23], v[4:7], v[230:233], v[8:11]
	global_load_dwordx4 v[4:7], v[172:173], off
	s_waitcnt vmcnt(0)
	v_mfma_f32_16x16x32_bf16 v[16:19], v[4:7], v[230:233], v[12:15]
	global_load_dwordx4 v[4:7], v[174:175], off
	s_nop 1
	global_load_dwordx4 v[12:15], v[178:179], off
	s_waitcnt vmcnt(1)
	v_mfma_f32_16x16x32_bf16 v[8:11], v[4:7], v[230:233], v[222:225]
	global_load_dwordx4 v[4:7], v[176:177], off
	s_waitcnt vmcnt(1)
	v_mfma_f32_16x16x32_bf16 v[12:15], v[12:15], v[230:233], v[0:3]
	s_nop 2
	global_load_dwordx4 v[0:3], v[238:239], off
	s_waitcnt vmcnt(1)
	v_mfma_f32_16x16x32_bf16 v[4:7], v[4:7], v[230:233], v[226:229]
	global_load_dwordx4 v[222:225], v[60:61], off offset:48
	s_nop 1
	global_load_dwordx4 v[226:229], v[60:61], off offset:32
	global_load_dwordx4 v[230:233], v[60:61], off offset:16
	global_load_dwordx4 v[234:237], v[60:61], off
	s_waitcnt vmcnt(4)
	v_lshlrev_b32_e32 v48, 16, v0
	v_and_b32_e32 v0, 0xffff0000, v0
	s_waitcnt vmcnt(0)
	v_mul_f32_e32 v235, v235, v0
	v_lshlrev_b32_e32 v0, 16, v1
	v_mul_f32_e32 v181, v234, v48
	v_mul_f32_e32 v241, v236, v0
	v_and_b32_e32 v0, 0xffff0000, v1
	v_mov_b32_e32 v48, v182
	v_mul_f32_e32 v1, v237, v0
	v_lshlrev_b32_e32 v0, 16, v2
	v_pk_add_f32 v[180:181], v[48:49], v[180:181]
	v_mov_b32_e32 v234, v183
	v_mul_f32_e32 v237, v230, v0
	v_and_b32_e32 v0, 0xffff0000, v2
	v_pk_add_f32 v[180:181], v[234:235], v[180:181]
	v_mul_f32_e32 v231, v231, v0
	v_pk_add_f32 v[180:181], v[240:241], v[180:181]
	v_mov_b32_e32 v0, v185
	v_pk_add_f32 v[0:1], v[0:1], v[180:181]
	v_mov_b32_e32 v236, v186
	v_pk_add_f32 v[0:1], v[236:237], v[0:1]
	v_mov_b32_e32 v230, v187
	v_pk_add_f32 v[180:181], v[230:231], v[0:1]
	v_lshlrev_b32_e32 v0, 16, v3
	v_mul_f32_e32 v183, v232, v0
	v_and_b32_e32 v0, 0xffff0000, v3
	v_mul_f32_e32 v185, v233, v0
	global_load_dwordx4 v[0:3], v[238:239], off offset:16
	v_mov_b32_e32 v182, v188
	v_pk_add_f32 v[180:181], v[182:183], v[180:181]
	v_mov_b32_e32 v186, v190
	v_pk_add_f32 v[180:181], v[184:185], v[180:181]
	v_mov_b32_e32 v230, v192
	v_mov_b32_e32 v232, v196
	s_waitcnt vmcnt(0)
	v_lshlrev_b32_e32 v48, 16, v0
	v_and_b32_e32 v0, 0xffff0000, v0
	v_mul_f32_e32 v227, v227, v0
	v_lshlrev_b32_e32 v0, 16, v1
	v_mul_f32_e32 v231, v228, v0
	v_and_b32_e32 v0, 0xffff0000, v1
	v_mul_f32_e32 v1, v229, v0
	v_lshlrev_b32_e32 v0, 16, v2
	v_mul_f32_e32 v187, v226, v48
	v_mul_f32_e32 v229, v222, v0
	v_and_b32_e32 v0, 0xffff0000, v2
	v_mul_f32_e32 v223, v223, v0
	v_lshlrev_b32_e32 v0, 16, v3
	v_pk_add_f32 v[180:181], v[186:187], v[180:181]
	v_mov_b32_e32 v226, v191
	v_mul_f32_e32 v233, v224, v0
	v_and_b32_e32 v0, 0xffff0000, v3
	v_pk_add_f32 v[180:181], v[226:227], v[180:181]
	v_mul_f32_e32 v3, v225, v0
	v_pk_add_f32 v[180:181], v[230:231], v[180:181]
	v_mov_b32_e32 v0, v193
	v_pk_add_f32 v[0:1], v[0:1], v[180:181]
	v_mov_b32_e32 v228, v194
	v_pk_add_f32 v[0:1], v[228:229], v[0:1]
	v_mov_b32_e32 v222, v195
	v_pk_add_f32 v[0:1], v[222:223], v[0:1]
	v_mov_b32_e32 v2, v197
	v_pk_add_f32 v[0:1], v[232:233], v[0:1]
	v_lshl_add_u64 v[180:181], v[66:67], 0, s[22:23]
	v_pk_add_f32 v[0:1], v[2:3], v[0:1]
	ds_bpermute_b32 v2, v217, v0
	ds_bpermute_b32 v3, v217, v1
	s_waitcnt lgkmcnt(0)
	v_pk_add_f32 v[0:1], v[0:1], v[2:3]
	ds_bpermute_b32 v2, v218, v0
	ds_bpermute_b32 v3, v218, v1
	s_waitcnt lgkmcnt(0)
	v_pk_add_f32 v[0:1], v[0:1], v[2:3]
	s_nop 0
	v_fmac_f32_e32 v0, v198, v1
	ds_read_b32 v1, v220 offset:1024
	s_waitcnt lgkmcnt(0)
	v_add_f32_e32 v1, v221, v1
	v_mul_f32_e32 v1, 0xbfb8aa3b, v1
	v_exp_f32_e32 v1, v1
	s_nop 0
	v_max_f32_e64 v0, |v0|, v1
	v_rcp_f32_e32 v48, v0
	v_lshl_add_u64 v[0:1], s[2:3], 0, v[40:41]
	v_lshl_add_u64 v[182:183], v[0:1], 0, s[0:1]
	s_mov_b32 s0, 0x6c01000
	v_add_co_u32_e64 v0, s[0:1], s0, v0
	v_pk_mul_f32 v[220:221], v[32:33], v[48:49] op_sel_hi:[1,0]
	s_nop 0
	v_addc_co_u32_e64 v1, s[0:1], 0, v1, s[0:1]
	global_load_dwordx2 v[0:1], v[0:1], off offset:32
	v_add_f32_e32 v198, 0, v220
	v_add_f32_e32 v198, v221, v198
	v_pk_mul_f32 v[220:221], v[28:29], v[48:49] op_sel_hi:[1,0]
	v_pk_mul_f32 v[194:195], v[4:5], v[48:49] op_sel_hi:[1,0]
	v_pk_mul_f32 v[192:193], v[6:7], v[48:49] op_sel_hi:[1,0]
	v_pk_mul_f32 v[190:191], v[12:13], v[48:49] op_sel_hi:[1,0]
	v_pk_mul_f32 v[188:189], v[14:15], v[48:49] op_sel_hi:[1,0]
	s_mov_b32 s0, 0x800000
	s_waitcnt vmcnt(0)
	v_lshlrev_b32_e32 v184, 16, v0
	v_mul_f32_e32 v184, 0xbfb8aa3b, v184
	v_exp_f32_e32 v184, v184
	v_and_b32_e32 v185, 0xffff0000, v0
	v_lshlrev_b32_e32 v196, 16, v1
	v_and_b32_e32 v197, 0xffff0000, v1
	v_add_f32_e32 v184, 1.0, v184
	v_rcp_f32_e32 v186, v184
	v_mul_f32_e32 v184, 0xbfb8aa3b, v185
	v_exp_f32_e32 v184, v184
	v_mul_f32_e32 v185, 0xbfb8aa3b, v197
	global_load_dwordx4 v[0:3], v[64:65], off
	v_exp_f32_e32 v185, v185
	v_add_f32_e32 v184, 1.0, v184
	v_rcp_f32_e32 v187, v184
	v_mul_f32_e32 v184, 0xbfb8aa3b, v196
	v_pk_mul_f32 v[196:197], v[34:35], v[48:49] op_sel_hi:[1,0]
	v_exp_f32_e32 v184, v184
	v_add_f32_e32 v196, v196, v198
	v_add_f32_e32 v198, v197, v196
	v_add_f32_e32 v198, v220, v198
	v_pk_mul_f32 v[196:197], v[30:31], v[48:49] op_sel_hi:[1,0]
	v_add_f32_e32 v198, v221, v198
	v_add_f32_e32 v196, v196, v198
	v_add_f32_e32 v198, v197, v196
	v_pk_mul_f32 v[220:221], v[24:25], v[48:49] op_sel_hi:[1,0]
	v_pk_mul_f32 v[196:197], v[26:27], v[48:49] op_sel_hi:[1,0]
	v_add_f32_e32 v198, v220, v198
	v_add_f32_e32 v198, v221, v198
	v_add_f32_e32 v196, v196, v198
	v_add_f32_e32 v198, v197, v196
	v_pk_mul_f32 v[220:221], v[20:21], v[48:49] op_sel_hi:[1,0]
	v_pk_mul_f32 v[196:197], v[22:23], v[48:49] op_sel_hi:[1,0]
	v_add_f32_e32 v198, v220, v198
	v_add_f32_e32 v198, v221, v198
	v_add_f32_e32 v196, v196, v198
	v_add_f32_e32 v198, v197, v196
	v_pk_mul_f32 v[220:221], v[16:17], v[48:49] op_sel_hi:[1,0]
	v_pk_mul_f32 v[196:197], v[18:19], v[48:49] op_sel_hi:[1,0]
	v_add_f32_e32 v198, v220, v198
	v_add_f32_e32 v198, v221, v198
	v_add_f32_e32 v196, v196, v198
	v_add_f32_e32 v198, v197, v196
	v_pk_mul_f32 v[220:221], v[8:9], v[48:49] op_sel_hi:[1,0]
	v_pk_mul_f32 v[196:197], v[10:11], v[48:49] op_sel_hi:[1,0]
	v_add_f32_e32 v198, v220, v198
	v_add_f32_e32 v198, v221, v198
	v_add_f32_e32 v196, v196, v198
	v_add_f32_e32 v196, v197, v196
	v_add_f32_e32 v194, v194, v196
	v_add_f32_e32 v194, v195, v194
	v_add_f32_e32 v192, v192, v194
	v_add_f32_e32 v192, v193, v192
	v_add_f32_e32 v190, v190, v192
	v_add_f32_e32 v190, v191, v190
	v_add_f32_e32 v188, v188, v190
	v_add_f32_e32 v188, v189, v188
	ds_bpermute_b32 v189, v217, v188
	v_add_f32_e32 v184, 1.0, v184
	v_add_f32_e32 v185, 1.0, v185
	v_rcp_f32_e32 v184, v184
	v_rcp_f32_e32 v185, v185
	s_waitcnt lgkmcnt(0)
	v_add_f32_e32 v188, v188, v189
	ds_bpermute_b32 v189, v218, v188
	s_waitcnt lgkmcnt(0)
	v_add_f32_e32 v188, v188, v189
	v_mul_f32_e32 v192, 0x3c000000, v188
	v_pk_fma_f32 v[190:191], v[32:33], v[48:49], v[192:193] op_sel_hi:[1,0,0] neg_lo:[0,0,1] neg_hi:[0,0,1]
	v_pk_fma_f32 v[188:189], v[34:35], v[48:49], v[192:193] op_sel_hi:[1,0,0] neg_lo:[0,0,1] neg_hi:[0,0,1]
	v_pk_mul_f32 v[194:195], v[190:191], v[190:191]
	v_pk_mul_f32 v[196:197], v[188:189], v[188:189]
	v_pk_fma_f32 v[34:35], v[28:29], v[48:49], v[192:193] op_sel_hi:[1,0,0] neg_lo:[0,0,1] neg_hi:[0,0,1]
	v_pk_fma_f32 v[32:33], v[30:31], v[48:49], v[192:193] op_sel_hi:[1,0,0] neg_lo:[0,0,1] neg_hi:[0,0,1]
	v_pk_fma_f32 v[30:31], v[24:25], v[48:49], v[192:193] op_sel_hi:[1,0,0] neg_lo:[0,0,1] neg_hi:[0,0,1]
	v_pk_fma_f32 v[28:29], v[26:27], v[48:49], v[192:193] op_sel_hi:[1,0,0] neg_lo:[0,0,1] neg_hi:[0,0,1]
	v_pk_fma_f32 v[26:27], v[20:21], v[48:49], v[192:193] op_sel_hi:[1,0,0] neg_lo:[0,0,1] neg_hi:[0,0,1]
	v_pk_fma_f32 v[24:25], v[22:23], v[48:49], v[192:193] op_sel_hi:[1,0,0] neg_lo:[0,0,1] neg_hi:[0,0,1]
	v_pk_fma_f32 v[22:23], v[16:17], v[48:49], v[192:193] op_sel_hi:[1,0,0] neg_lo:[0,0,1] neg_hi:[0,0,1]
	v_pk_fma_f32 v[20:21], v[18:19], v[48:49], v[192:193] op_sel_hi:[1,0,0] neg_lo:[0,0,1] neg_hi:[0,0,1]
	v_pk_fma_f32 v[18:19], v[8:9], v[48:49], v[192:193] op_sel_hi:[1,0,0] neg_lo:[0,0,1] neg_hi:[0,0,1]
	v_pk_fma_f32 v[16:17], v[10:11], v[48:49], v[192:193] op_sel_hi:[1,0,0] neg_lo:[0,0,1] neg_hi:[0,0,1]
	v_pk_fma_f32 v[10:11], v[12:13], v[48:49], v[192:193] op_sel_hi:[1,0,0] neg_lo:[0,0,1] neg_hi:[0,0,1]
	v_pk_fma_f32 v[8:9], v[14:15], v[48:49], v[192:193] op_sel_hi:[1,0,0] neg_lo:[0,0,1] neg_hi:[0,0,1]
	v_pk_fma_f32 v[6:7], v[6:7], v[48:49], v[192:193] op_sel_hi:[1,0,0] neg_lo:[0,0,1] neg_hi:[0,0,1]
	v_pk_fma_f32 v[4:5], v[4:5], v[48:49], v[192:193] op_sel_hi:[1,0,0] neg_lo:[0,0,1] neg_hi:[0,0,1]
	v_add_f32_e32 v48, v194, v195
	v_add_f32_e32 v48, v196, v48
	v_pk_mul_f32 v[220:221], v[34:35], v[34:35]
	v_add_f32_e32 v48, v197, v48
	v_add_f32_e32 v48, v220, v48
	v_pk_mul_f32 v[222:223], v[32:33], v[32:33]
	v_add_f32_e32 v48, v221, v48
	v_add_f32_e32 v48, v222, v48
	v_pk_mul_f32 v[224:225], v[30:31], v[30:31]
	v_add_f32_e32 v48, v223, v48
	v_add_f32_e32 v48, v224, v48
	v_pk_mul_f32 v[226:227], v[28:29], v[28:29]
	v_add_f32_e32 v48, v225, v48
	v_add_f32_e32 v48, v226, v48
	v_pk_mul_f32 v[228:229], v[26:27], v[26:27]
	v_add_f32_e32 v48, v227, v48
	v_add_f32_e32 v48, v228, v48
	v_pk_mul_f32 v[230:231], v[24:25], v[24:25]
	v_add_f32_e32 v48, v229, v48
	v_add_f32_e32 v48, v230, v48
	v_pk_mul_f32 v[232:233], v[22:23], v[22:23]
	v_add_f32_e32 v48, v231, v48
	v_add_f32_e32 v48, v232, v48
	v_pk_mul_f32 v[234:235], v[20:21], v[20:21]
	v_add_f32_e32 v48, v233, v48
	v_add_f32_e32 v48, v234, v48
	v_pk_mul_f32 v[236:237], v[18:19], v[18:19]
	v_add_f32_e32 v48, v235, v48
	v_add_f32_e32 v48, v236, v48
	v_pk_mul_f32 v[238:239], v[16:17], v[16:17]
	v_add_f32_e32 v48, v237, v48
	v_add_f32_e32 v48, v238, v48
	v_pk_mul_f32 v[192:193], v[4:5], v[4:5]
	v_add_f32_e32 v48, v239, v48
	v_add_f32_e32 v48, v192, v48
	v_pk_mul_f32 v[240:241], v[6:7], v[6:7]
	v_add_f32_e32 v48, v193, v48
	v_add_f32_e32 v48, v240, v48
	v_pk_mul_f32 v[12:13], v[10:11], v[10:11]
	v_add_f32_e32 v48, v241, v48
	v_add_f32_e32 v12, v12, v48
	v_pk_mul_f32 v[14:15], v[8:9], v[8:9]
	v_add_f32_e32 v12, v13, v12
	v_add_f32_e32 v12, v14, v12
	v_add_f32_e32 v12, v15, v12
	ds_bpermute_b32 v13, v217, v12
	s_waitcnt lgkmcnt(0)
	v_add_f32_e32 v12, v12, v13
	ds_bpermute_b32 v13, v218, v12
	s_waitcnt lgkmcnt(0)
	v_add_f32_e32 v12, v12, v13
	v_fmamk_f32 v12, v12, 0x3c000000, v206
	v_cmp_gt_f32_e64 s[22:23], s0, v12
	v_mul_f32_e32 v13, 0x4b800000, v12
	s_mov_b64 s[0:1], 0
	v_cndmask_b32_e64 v12, v12, v13, s[22:23]
	v_rsq_f32_e32 v12, v12
	s_nop 0
	v_mul_f32_e32 v13, 0x45800000, v12
	v_cndmask_b32_e64 v12, v12, v13, s[22:23]
	v_pk_mul_f32 v[14:15], v[190:191], v[12:13] op_sel_hi:[1,0]
	s_waitcnt vmcnt(0)
	v_pk_mul_f32 v[0:1], v[0:1], v[14:15]
	v_pk_mul_f32 v[14:15], v[188:189], v[12:13] op_sel_hi:[1,0]
	v_pk_mul_f32 v[0:1], v[186:187], v[0:1]
	v_pk_mul_f32 v[2:3], v[2:3], v[14:15]
	v_cvt_pk_bf16_f32 v0, v0, v1
	v_pk_mul_f32 v[2:3], v[184:185], v[2:3]
	s_nop 0
	v_cvt_pk_bf16_f32 v1, v2, v3
	global_store_dwordx2 v[180:181], v[0:1], off
	global_load_dwordx2 v[244:245], v[182:183], off offset:32
	global_load_dwordx4 v[0:3], v[64:65], off offset:64
	s_waitcnt vmcnt(0)
	v_lshlrev_b32_e32 v13, 16, v244
	v_and_b32_e32 v15, 0xffff0000, v244
	v_lshlrev_b32_e32 v48, 16, v245
	v_and_b32_e32 v184, 0xffff0000, v245
	v_mul_f32_e32 v13, 0xbfb8aa3b, v13
	v_exp_f32_e32 v13, v13
	s_nop 0
	v_add_f32_e32 v13, 1.0, v13
	v_rcp_f32_e32 v14, v13
	v_pk_mul_f32 v[34:35], v[34:35], v[12:13] op_sel_hi:[1,0]
	v_mul_f32_e32 v13, 0xbfb8aa3b, v15
	v_exp_f32_e32 v13, v13
	s_waitcnt vmcnt(0)
	v_pk_mul_f32 v[0:1], v[0:1], v[34:35]
	v_add_f32_e32 v13, 1.0, v13
	v_rcp_f32_e32 v15, v13
	v_mul_f32_e32 v13, 0xbfb8aa3b, v48
	v_exp_f32_e32 v13, v13
	v_pk_mul_f32 v[0:1], v[14:15], v[0:1]
	s_nop 0
	v_cvt_pk_bf16_f32 v0, v0, v1
	v_add_f32_e32 v13, 1.0, v13
	v_rcp_f32_e32 v14, v13
	v_pk_mul_f32 v[32:33], v[32:33], v[12:13] op_sel_hi:[1,0]
	v_mul_f32_e32 v13, 0xbfb8aa3b, v184
	v_exp_f32_e32 v13, v13
	v_pk_mul_f32 v[2:3], v[2:3], v[32:33]
	v_add_f32_e32 v13, 1.0, v13
	v_rcp_f32_e32 v15, v13
	s_nop 0
	v_pk_mul_f32 v[2:3], v[14:15], v[2:3]
	s_nop 0
	v_cvt_pk_bf16_f32 v1, v2, v3
	global_store_dwordx2 v[180:181], v[0:1], off offset:32
	global_load_dwordx2 v[244:245], v[182:183], off offset:64
	global_load_dwordx4 v[0:3], v[64:65], off offset:128
	s_waitcnt vmcnt(0)
	v_lshlrev_b32_e32 v13, 16, v244
	v_and_b32_e32 v15, 0xffff0000, v244
	v_lshlrev_b32_e32 v32, 16, v245
	v_and_b32_e32 v33, 0xffff0000, v245
	v_mul_f32_e32 v13, 0xbfb8aa3b, v13
	v_exp_f32_e32 v13, v13
	s_nop 0
	v_add_f32_e32 v13, 1.0, v13
	v_rcp_f32_e32 v14, v13
	v_pk_mul_f32 v[30:31], v[30:31], v[12:13] op_sel_hi:[1,0]
	v_mul_f32_e32 v13, 0xbfb8aa3b, v15
	v_exp_f32_e32 v13, v13
	s_waitcnt vmcnt(0)
	v_pk_mul_f32 v[0:1], v[0:1], v[30:31]
	v_add_f32_e32 v13, 1.0, v13
	v_rcp_f32_e32 v15, v13
	v_mul_f32_e32 v13, 0xbfb8aa3b, v32
	v_exp_f32_e32 v13, v13
	v_pk_mul_f32 v[0:1], v[14:15], v[0:1]
	s_nop 0
	v_cvt_pk_bf16_f32 v0, v0, v1
	v_add_f32_e32 v13, 1.0, v13
	v_rcp_f32_e32 v14, v13
	v_pk_mul_f32 v[28:29], v[28:29], v[12:13] op_sel_hi:[1,0]
	v_mul_f32_e32 v13, 0xbfb8aa3b, v33
	v_exp_f32_e32 v13, v13
	v_pk_mul_f32 v[2:3], v[2:3], v[28:29]
	v_add_f32_e32 v13, 1.0, v13
	v_rcp_f32_e32 v15, v13
	s_nop 0
	v_pk_mul_f32 v[2:3], v[14:15], v[2:3]
	s_nop 0
	v_cvt_pk_bf16_f32 v1, v2, v3
	global_store_dwordx2 v[180:181], v[0:1], off offset:64
	global_load_dwordx2 v[244:245], v[182:183], off offset:96
	global_load_dwordx4 v[0:3], v[64:65], off offset:192
	s_waitcnt vmcnt(0)
	v_lshlrev_b32_e32 v13, 16, v244
	v_and_b32_e32 v15, 0xffff0000, v244
	v_lshlrev_b32_e32 v28, 16, v245
	v_and_b32_e32 v29, 0xffff0000, v245
	v_mul_f32_e32 v13, 0xbfb8aa3b, v13
	v_exp_f32_e32 v13, v13
	s_nop 0
	v_add_f32_e32 v13, 1.0, v13
	v_rcp_f32_e32 v14, v13
	v_pk_mul_f32 v[26:27], v[26:27], v[12:13] op_sel_hi:[1,0]
	v_mul_f32_e32 v13, 0xbfb8aa3b, v15
	v_exp_f32_e32 v13, v13
	s_waitcnt vmcnt(0)
	v_pk_mul_f32 v[0:1], v[0:1], v[26:27]
	v_add_f32_e32 v13, 1.0, v13
	v_rcp_f32_e32 v15, v13
	v_mul_f32_e32 v13, 0xbfb8aa3b, v28
	v_exp_f32_e32 v13, v13
	v_pk_mul_f32 v[0:1], v[14:15], v[0:1]
	s_nop 0
	v_cvt_pk_bf16_f32 v0, v0, v1
	v_add_f32_e32 v13, 1.0, v13
	v_rcp_f32_e32 v14, v13
	v_pk_mul_f32 v[24:25], v[24:25], v[12:13] op_sel_hi:[1,0]
	v_mul_f32_e32 v13, 0xbfb8aa3b, v29
	v_exp_f32_e32 v13, v13
	v_pk_mul_f32 v[2:3], v[2:3], v[24:25]
	v_add_f32_e32 v13, 1.0, v13
	v_rcp_f32_e32 v15, v13
	s_nop 0
	v_pk_mul_f32 v[2:3], v[14:15], v[2:3]
	s_nop 0
	v_cvt_pk_bf16_f32 v1, v2, v3
	global_store_dwordx2 v[180:181], v[0:1], off offset:96
	global_load_dwordx2 v[244:245], v[182:183], off offset:128
	global_load_dwordx4 v[0:3], v[64:65], off offset:256
	s_waitcnt vmcnt(0)
	v_lshlrev_b32_e32 v13, 16, v244
	v_and_b32_e32 v15, 0xffff0000, v244
	v_lshlrev_b32_e32 v24, 16, v245
	v_and_b32_e32 v25, 0xffff0000, v245
	v_mul_f32_e32 v13, 0xbfb8aa3b, v13
	v_exp_f32_e32 v13, v13
	s_nop 0
	v_add_f32_e32 v13, 1.0, v13
	v_rcp_f32_e32 v14, v13
	v_pk_mul_f32 v[22:23], v[22:23], v[12:13] op_sel_hi:[1,0]
	v_mul_f32_e32 v13, 0xbfb8aa3b, v15
	v_exp_f32_e32 v13, v13
	s_waitcnt vmcnt(0)
	v_pk_mul_f32 v[0:1], v[0:1], v[22:23]
	v_add_f32_e32 v13, 1.0, v13
	v_rcp_f32_e32 v15, v13
	v_mul_f32_e32 v13, 0xbfb8aa3b, v24
	v_exp_f32_e32 v13, v13
	v_pk_mul_f32 v[0:1], v[14:15], v[0:1]
	s_nop 0
	v_cvt_pk_bf16_f32 v0, v0, v1
	v_add_f32_e32 v13, 1.0, v13
	v_rcp_f32_e32 v14, v13
	v_pk_mul_f32 v[20:21], v[20:21], v[12:13] op_sel_hi:[1,0]
	v_mul_f32_e32 v13, 0xbfb8aa3b, v25
	v_exp_f32_e32 v13, v13
	v_pk_mul_f32 v[2:3], v[2:3], v[20:21]
	v_add_f32_e32 v13, 1.0, v13
	v_rcp_f32_e32 v15, v13
	s_nop 0
	v_pk_mul_f32 v[2:3], v[14:15], v[2:3]
	s_nop 0
	v_cvt_pk_bf16_f32 v1, v2, v3
	global_store_dwordx2 v[180:181], v[0:1], off offset:128
	global_load_dwordx2 v[244:245], v[182:183], off offset:160
	global_load_dwordx4 v[0:3], v[64:65], off offset:320
	s_waitcnt vmcnt(0)
	v_lshlrev_b32_e32 v13, 16, v244
	v_and_b32_e32 v15, 0xffff0000, v244
	v_lshlrev_b32_e32 v20, 16, v245
	v_and_b32_e32 v21, 0xffff0000, v245
	v_mul_f32_e32 v13, 0xbfb8aa3b, v13
	v_exp_f32_e32 v13, v13
	s_nop 0
	v_add_f32_e32 v13, 1.0, v13
	v_rcp_f32_e32 v14, v13
	v_pk_mul_f32 v[18:19], v[18:19], v[12:13] op_sel_hi:[1,0]
	v_mul_f32_e32 v13, 0xbfb8aa3b, v15
	v_exp_f32_e32 v13, v13
	s_waitcnt vmcnt(0)
	v_pk_mul_f32 v[0:1], v[0:1], v[18:19]
	v_add_f32_e32 v13, 1.0, v13
	v_rcp_f32_e32 v15, v13
	v_mul_f32_e32 v13, 0xbfb8aa3b, v20
	v_exp_f32_e32 v13, v13
	v_pk_mul_f32 v[0:1], v[14:15], v[0:1]
	s_nop 0
	v_cvt_pk_bf16_f32 v0, v0, v1
	v_add_f32_e32 v13, 1.0, v13
	v_rcp_f32_e32 v14, v13
	v_pk_mul_f32 v[16:17], v[16:17], v[12:13] op_sel_hi:[1,0]
	v_mul_f32_e32 v13, 0xbfb8aa3b, v21
	v_exp_f32_e32 v13, v13
	v_pk_mul_f32 v[2:3], v[2:3], v[16:17]
	v_add_f32_e32 v13, 1.0, v13
	v_rcp_f32_e32 v15, v13
	s_nop 0
	v_pk_mul_f32 v[2:3], v[14:15], v[2:3]
	s_nop 0
	v_cvt_pk_bf16_f32 v1, v2, v3
	global_store_dwordx2 v[180:181], v[0:1], off offset:160
	global_load_dwordx2 v[244:245], v[182:183], off offset:192
	global_load_dwordx4 v[0:3], v[64:65], off offset:384
	s_waitcnt vmcnt(0)
	v_lshlrev_b32_e32 v13, 16, v244
	v_and_b32_e32 v15, 0xffff0000, v244
	v_lshlrev_b32_e32 v16, 16, v245
	v_and_b32_e32 v17, 0xffff0000, v245
	v_mul_f32_e32 v13, 0xbfb8aa3b, v13
	v_exp_f32_e32 v13, v13
	s_nop 0
	v_add_f32_e32 v13, 1.0, v13
	v_pk_mul_f32 v[4:5], v[4:5], v[12:13] op_sel_hi:[1,0]
	v_rcp_f32_e32 v14, v13
	v_pk_mul_f32 v[6:7], v[6:7], v[12:13] op_sel_hi:[1,0]
	s_waitcnt vmcnt(0)
	v_pk_mul_f32 v[0:1], v[0:1], v[4:5]
	v_mul_f32_e32 v4, 0xbfb8aa3b, v15
	v_exp_f32_e32 v4, v4
	v_mul_f32_e32 v5, 0xbfb8aa3b, v17
	v_exp_f32_e32 v5, v5
	v_pk_mul_f32 v[2:3], v[2:3], v[6:7]
	v_add_f32_e32 v4, 1.0, v4
	v_rcp_f32_e32 v15, v4
	v_mul_f32_e32 v4, 0xbfb8aa3b, v16
	v_exp_f32_e32 v4, v4
	v_add_f32_e32 v5, 1.0, v5
	v_rcp_f32_e32 v5, v5
	v_pk_mul_f32 v[0:1], v[14:15], v[0:1]
	v_add_f32_e32 v4, 1.0, v4
	v_rcp_f32_e32 v4, v4
	v_cvt_pk_bf16_f32 v0, v0, v1
	v_pk_mul_f32 v[2:3], v[4:5], v[2:3]
	s_nop 0
	v_cvt_pk_bf16_f32 v1, v2, v3
	global_store_dwordx2 v[180:181], v[0:1], off offset:192
	global_load_dwordx2 v[244:245], v[182:183], off offset:224
	global_load_dwordx4 v[0:3], v[64:65], off offset:448
	s_waitcnt vmcnt(0)
	v_lshlrev_b32_e32 v4, 16, v244
	v_and_b32_e32 v5, 0xffff0000, v244
	v_lshlrev_b32_e32 v13, 16, v245
	v_and_b32_e32 v14, 0xffff0000, v245
	v_mul_f32_e32 v4, 0xbfb8aa3b, v4
	v_mul_f32_e32 v5, 0xbfb8aa3b, v5
	v_exp_f32_e32 v4, v4
	v_exp_f32_e32 v5, v5
	v_pk_mul_f32 v[6:7], v[10:11], v[12:13] op_sel_hi:[1,0]
	v_add_f32_e32 v4, 1.0, v4
	v_add_f32_e32 v5, 1.0, v5
	v_rcp_f32_e32 v4, v4
	v_rcp_f32_e32 v5, v5
	s_waitcnt vmcnt(0)
	v_pk_mul_f32 v[0:1], v[0:1], v[6:7]
	s_nop 0
	v_pk_mul_f32 v[0:1], v[4:5], v[0:1]
	v_mul_f32_e32 v4, 0xbfb8aa3b, v13
	v_mul_f32_e32 v5, 0xbfb8aa3b, v14
	v_exp_f32_e32 v4, v4
	v_exp_f32_e32 v5, v5
	v_pk_mul_f32 v[6:7], v[8:9], v[12:13] op_sel_hi:[1,0]
	v_cvt_pk_bf16_f32 v0, v0, v1
	v_add_f32_e32 v4, 1.0, v4
	v_add_f32_e32 v5, 1.0, v5
	v_rcp_f32_e32 v4, v4
	v_rcp_f32_e32 v5, v5
	v_pk_mul_f32 v[2:3], v[2:3], v[6:7]
	s_nop 0
	v_pk_mul_f32 v[2:3], v[4:5], v[2:3]
	s_nop 0
	v_cvt_pk_bf16_f32 v1, v2, v3
	global_store_dwordx2 v[180:181], v[0:1], off offset:224
	s_cbranch_vccz .LBB0_506
	s_add_i32 s84, s84, s96
	s_cmpk_gt_i32 s84, 0x3ff
	s_cbranch_scc0 .LBB0_501
